# seam barrier: non-last workgroups of an XCD poll the top generation word directly (one hop fewer on release); deferred SSQ atomics kept
# speedup vs baseline: 1.0046x; 1.0036x over previous
; __device__ __forceinline__ unsigned xb_ld(unsigned* p)              { return __hip_atomic_load(p, __ATOMIC_RELAXED, __HIP_MEMORY_SCOPE_AGENT); }
; __device__ __forceinline__ unsigned xb_add(unsigned* p, unsigned v) { return __hip_atomic_fetch_add(p, v, __ATOMIC_RELAXED, __HIP_MEMORY_SCOPE_AGENT); }
; #define XB_SPIN(cond, bar) do { unsigned _sp = 0; while (cond) { __builtin_amdgcn_s_sleep(1); \
;     if ((++_sp & 255u) == 0u) { if (xb_ld(&(bar)[XB_TMO])) break; if (_sp > XB_SPIN_CAP) { atomicAdd(&(bar)[XB_TMO], 1u); break; } } } } while (0)
; __device__ __forceinline__ void xcd_barrier(unsigned* bar, volatile LAS unsigned* st, bool lead) {
;     ...
;         const unsigned old = xb_add(&bar[XB_XSUB(x)], 1u);
;         const unsigned gen = old / nloc;
;         if (old + 1u == (gen + 1u) * nloc) {
;             __builtin_amdgcn_fence(__ATOMIC_RELEASE, "agent");
;             asm volatile("s_waitcnt vmcnt(0)" ::: "memory");
;             const unsigned og = xb_add(&bar[XB_TOP], 1u);
;             const unsigned tg = og / nx;
;             if (og + 1u == (tg + 1u) * nx) xb_add(&bar[XB_TOPGEN], 1u);
;             else XB_SPIN(xb_ld(&bar[XB_TOPGEN]) == tg, bar);
;             __builtin_amdgcn_fence(__ATOMIC_ACQUIRE, "agent");
;             xb_add(&bar[XB_XGEN(x)], 1u);
;             asm volatile("s_waitcnt vmcnt(0)" ::: "memory");
;         } else {
;             XB_SPIN(xb_ld(&bar[XB_XGEN(x)]) == gen, bar);
.LBB0_230:
	s_lshl_b32 s0, s3, 8
	s_add_u32 s22, s38, s0
	s_addc_u32 s3, s39, 0
	v_mov_b32_e32 v1, s22
	v_add_co_u32_e32 v4, vcc, 0x1000, v1
	v_mov_b32_e32 v1, s3
	s_nop 0
	v_addc_co_u32_e32 v5, vcc, 0, v1, vcc
	v_mov_b32_e32 v1, 1
	global_atomic_add v1, v[4:5], v1, off offset:1024 sc0
	v_cvt_f32_u32_e32 v3, v2
	v_sub_u32_e32 v4, 0, v2
	v_rcp_iflag_f32_e32 v3, v3
	s_nop 0
	v_mul_f32_e32 v3, 0x4f7ffffe, v3
	v_cvt_u32_f32_e32 v3, v3
	v_mul_lo_u32 v4, v4, v3
	v_mul_hi_u32 v4, v3, v4
	v_add_u32_e32 v3, v3, v4
	s_waitcnt vmcnt(0) lgkmcnt(0)
	v_mul_hi_u32 v3, v1, v3
	v_mul_lo_u32 v5, v3, v2
	v_add_u32_e32 v4, 1, v1
	v_sub_u32_e32 v1, v1, v5
	v_add_u32_e32 v6, 1, v3
	v_cmp_ge_u32_e32 vcc, v1, v2
	v_sub_u32_e32 v5, v1, v2
	s_nop 0
	v_cndmask_b32_e32 v3, v3, v6, vcc
	v_cndmask_b32_e32 v1, v1, v5, vcc
	v_add_u32_e32 v5, 1, v3
	v_cmp_ge_u32_e32 vcc, v1, v2
	s_nop 1
	v_cndmask_b32_e32 v1, v3, v5, vcc
	v_mad_u64_u32 v[2:3], s[0:1], v2, v1, v[2:3]
	v_cmp_ne_u32_e32 vcc, v4, v2
	s_and_saveexec_b64 s[0:1], vcc
	s_xor_b64 s[0:1], exec, s[0:1]
	s_cbranch_execz .LBB0_243
	v_mov_b32_e32 v0, s38
	v_add_co_u32_e32 v2, vcc, 0x3000, v0
	v_mov_b32_e32 v0, s39
	s_nop 0
	v_addc_co_u32_e32 v3, vcc, 0, v0, vcc
	global_load_dword v0, v[2:3], off offset:1280 sc1
	s_add_u32 s6, s38, 0x3500
	s_addc_u32 s7, s39, 0
	s_waitcnt vmcnt(0) lgkmcnt(0)
	v_cmp_eq_u32_e32 vcc, v0, v1
	s_and_saveexec_b64 s[4:5], vcc
	s_cbranch_execz .LBB0_242
	s_mov_b32 s23, 1
	s_mov_b64 s[8:9], 0
	s_branch .LBB0_234

; __device__ __forceinline__ unsigned xb_ld(unsigned* p)              { return __hip_atomic_load(p, __ATOMIC_RELAXED, __HIP_MEMORY_SCOPE_AGENT); }
; __device__ __forceinline__ unsigned xb_add(unsigned* p, unsigned v) { return __hip_atomic_fetch_add(p, v, __ATOMIC_RELAXED, __HIP_MEMORY_SCOPE_AGENT); }
; #define XB_SPIN(cond, bar) do { unsigned _sp = 0; while (cond) { __builtin_amdgcn_s_sleep(1); \
;     if ((++_sp & 255u) == 0u) { if (xb_ld(&(bar)[XB_TMO])) break; if (_sp > XB_SPIN_CAP) { atomicAdd(&(bar)[XB_TMO], 1u); break; } } } } while (0)
; __device__ __forceinline__ void xcd_barrier(unsigned* bar, volatile LAS unsigned* st, bool lead) {
;     ...
;         const unsigned old = xb_add(&bar[XB_XSUB(x)], 1u);
;         const unsigned gen = old / nloc;
;         if (old + 1u == (gen + 1u) * nloc) {
;             __builtin_amdgcn_fence(__ATOMIC_RELEASE, "agent");
;             asm volatile("s_waitcnt vmcnt(0)" ::: "memory");
;             const unsigned og = xb_add(&bar[XB_TOP], 1u);
;             const unsigned tg = og / nx;
;             if (og + 1u == (tg + 1u) * nx) xb_add(&bar[XB_TOPGEN], 1u);
;             else XB_SPIN(xb_ld(&bar[XB_TOPGEN]) == tg, bar);
;             __builtin_amdgcn_fence(__ATOMIC_ACQUIRE, "agent");
;             xb_add(&bar[XB_XGEN(x)], 1u);
;             asm volatile("s_waitcnt vmcnt(0)" ::: "memory");
;         } else {
;             XB_SPIN(xb_ld(&bar[XB_XGEN(x)]) == gen, bar);
.LBB0_538:
	s_lshl_b32 s0, s3, 8
	s_add_u32 s22, s36, s0
	s_addc_u32 s3, s37, 0
	v_mov_b32_e32 v1, s22
	v_add_co_u32_e32 v4, vcc, 0x1000, v1
	v_mov_b32_e32 v1, s3
	s_nop 0
	v_addc_co_u32_e32 v5, vcc, 0, v1, vcc
	v_mov_b32_e32 v1, 1
	global_atomic_add v1, v[4:5], v1, off offset:1024 sc0
	v_cvt_f32_u32_e32 v3, v2
	v_sub_u32_e32 v4, 0, v2
	v_rcp_iflag_f32_e32 v3, v3
	s_nop 0
	v_mul_f32_e32 v3, 0x4f7ffffe, v3
	v_cvt_u32_f32_e32 v3, v3
	v_mul_lo_u32 v4, v4, v3
	v_mul_hi_u32 v4, v3, v4
	v_add_u32_e32 v3, v3, v4
	s_waitcnt vmcnt(0) lgkmcnt(0)
	v_mul_hi_u32 v3, v1, v3
	v_mul_lo_u32 v5, v3, v2
	v_add_u32_e32 v4, 1, v1
	v_sub_u32_e32 v1, v1, v5
	v_add_u32_e32 v6, 1, v3
	v_cmp_ge_u32_e32 vcc, v1, v2
	v_sub_u32_e32 v5, v1, v2
	s_nop 0
	v_cndmask_b32_e32 v3, v3, v6, vcc
	v_cndmask_b32_e32 v1, v1, v5, vcc
	v_add_u32_e32 v5, 1, v3
	v_cmp_ge_u32_e32 vcc, v1, v2
	s_nop 1
	v_cndmask_b32_e32 v1, v3, v5, vcc
	v_mad_u64_u32 v[2:3], s[0:1], v2, v1, v[2:3]
	v_cmp_ne_u32_e32 vcc, v4, v2
	s_and_saveexec_b64 s[0:1], vcc
	s_xor_b64 s[0:1], exec, s[0:1]
	s_cbranch_execz .LBB0_551
	v_mov_b32_e32 v0, s36
	v_add_co_u32_e32 v2, vcc, 0x3000, v0
	v_mov_b32_e32 v0, s37
	s_nop 0
	v_addc_co_u32_e32 v3, vcc, 0, v0, vcc
	global_load_dword v0, v[2:3], off offset:1280 sc1
	s_add_u32 s6, s36, 0x3500
	s_addc_u32 s7, s37, 0
	s_waitcnt vmcnt(0) lgkmcnt(0)
	v_cmp_eq_u32_e32 vcc, v0, v1
	s_and_saveexec_b64 s[4:5], vcc
	s_cbranch_execz .LBB0_550
	s_mov_b32 s23, 1
	s_mov_b64 s[8:9], 0
	s_branch .LBB0_542
